# G1 in-projection GEMM: 5 full rounds (1280 tiles) in the G1 phase; the remaining 128 tiles (made UZ-only by swapping column tiles 17 and 21 in the tile order) computed during MIX2 by attention workgro
# speedup vs baseline: 1.0227x; 1.0227x over previous
.LBB0_159:
	s_add_i32 s60, s60, 1
	s_mul_i32 s23, s60, s75
	s_mul_hi_u32 s25, s60, s74
	s_add_i32 s25, s25, s23
	s_mul_i32 s23, s60, s74
	s_add_u32 s26, s23, s72
	s_addc_u32 s27, s25, s73
	v_mov_b64_e32 v[8:9], 0x500
	v_cmp_lt_i64_e64 s[42:43], s[26:27], v[8:9]
	v_mov_b64_e32 v[8:9], 0x4ff
	v_cmp_gt_i64_e32 vcc, s[26:27], v[8:9]
	s_cbranch_vccnz .LBB0_161
	s_ashr_i32 s22, s26, 31
	s_lshr_b32 s22, s22, 29
	s_add_i32 s22, s26, s22
	s_ashr_i32 s23, s22, 3
	s_and_b32 s22, s22, -8
	s_sub_i32 s22, s26, s22
	s_cmp_lt_i32 s22, 0
	s_movk_i32 s24, 0xb1
	s_cselect_b32 s24, s24, 0xb0
	s_mul_i32 s22, s24, s22
	s_add_i32 s22, s22, s23
	s_mul_hi_i32 s23, s22, 0x2e8ba2e9
	s_lshr_b32 s24, s23, 31
	s_ashr_i32 s23, s23, 5
	s_add_i32 s23, s23, s24
	s_lshl_b32 s24, s23, 3
	s_sub_i32 s25, 64, s24
	s_min_i32 s25, s25, 8
	s_abs_i32 s26, s25
	v_cvt_f32_u32_e32 v8, s26
	s_sub_i32 s28, 0, s26
	s_mulk_i32 s23, 0xb0
	s_sub_i32 s23, s22, s23
	v_rcp_iflag_f32_e32 v8, v8
	s_abs_i32 s22, s23
	s_xor_b32 s27, s23, s25
	s_ashr_i32 s27, s27, 31
	v_mul_f32_e32 v8, 0x4f7ffffe, v8
	v_cvt_u32_f32_e32 v8, v8
	s_nop 0
	v_readfirstlane_b32 s29, v8
	s_mul_i32 s28, s28, s29
	s_mul_hi_u32 s28, s29, s28
	s_add_i32 s29, s29, s28
	s_mul_hi_u32 s28, s22, s29
	s_mul_i32 s29, s28, s26
	s_sub_i32 s22, s22, s29
	s_add_i32 s34, s28, 1
	s_sub_i32 s29, s22, s26
	s_cmp_ge_u32 s22, s26
	s_cselect_b32 s28, s34, s28
	s_cselect_b32 s22, s29, s22
	s_add_i32 s29, s28, 1
	s_cmp_ge_u32 s22, s26
	s_cselect_b32 s22, s29, s28
	s_xor_b32 s22, s22, s27
	s_sub_i32 s22, s22, s27
	s_mul_i32 s25, s22, s25
	s_sub_i32 s23, s23, s25
	s_add_i32 s24, s23, s24
.LBB0_161:
	s_cmp_eq_u32 s22, 21
	s_cselect_b32 s25, 17, s22
	s_cmp_eq_u32 s22, 17
	s_cselect_b32 s22, 21, s25
	s_ashr_i32 s25, s24, 31
	s_lshl_b64 s[26:27], s[24:25], 19
	s_add_u32 s26, s48, s26
	s_addc_u32 s27, s49, s27
	s_and_b64 s[28:29], s[42:43], exec
	s_cselect_b32 s25, s27, s31
	s_cselect_b32 s36, s26, s30
	s_ashr_i32 s23, s22, 31
	s_lshl_b64 s[28:29], s[22:23], 19
	s_add_u32 s28, s50, s28
	s_addc_u32 s29, s51, s29
	s_and_b64 s[34:35], s[42:43], exec
	s_cselect_b32 s23, s29, s1
	s_cselect_b32 s37, s28, s0
	s_add_u32 s38, s0, 0x100
	s_addc_u32 s39, s1, 0
	s_add_u32 s0, s30, 0x40080
	v_mov_b32_e32 v80, 0
	s_addc_u32 s1, s31, 0
	s_mov_b32 s44, -2
	v_mov_b32_e32 v81, v80
	v_mov_b32_e32 v82, v80
	v_mov_b32_e32 v83, v80
	v_mov_b32_e32 v84, v80
	v_mov_b32_e32 v85, v80
	v_mov_b32_e32 v86, v80
	v_mov_b32_e32 v87, v80
	v_mov_b32_e32 v88, v80
	v_mov_b32_e32 v89, v80
	s_waitcnt lgkmcnt(0)
	v_mov_b32_e32 v90, v80
	v_mov_b32_e32 v91, v80
	v_mov_b32_e32 v92, v80
	v_mov_b32_e32 v93, v80
	v_mov_b32_e32 v94, v80
	v_mov_b32_e32 v95, v80
	v_mov_b32_e32 v96, v80
	v_mov_b32_e32 v97, v80
	v_mov_b32_e32 v98, v80
	v_mov_b32_e32 v99, v80
	v_mov_b32_e32 v100, v80
	v_mov_b32_e32 v101, v80
	v_mov_b32_e32 v102, v80
	v_mov_b32_e32 v103, v80
	v_mov_b32_e32 v112, v80
	v_mov_b32_e32 v113, v80
	v_mov_b32_e32 v114, v80
	v_mov_b32_e32 v115, v80
	v_mov_b32_e32 v116, v80
	v_mov_b32_e32 v117, v80
	v_mov_b32_e32 v118, v80
	v_mov_b32_e32 v119, v80
	v_mov_b32_e32 v8, v80
	v_mov_b32_e32 v9, v80
	v_mov_b32_e32 v10, v80
	v_mov_b32_e32 v11, v80
	v_mov_b32_e32 v12, v80
	v_mov_b32_e32 v13, v80
	v_mov_b32_e32 v14, v80
	v_mov_b32_e32 v15, v80
	v_mov_b32_e32 v16, v80
	v_mov_b32_e32 v17, v80
	v_mov_b32_e32 v18, v80
	v_mov_b32_e32 v19, v80
	v_mov_b32_e32 v20, v80
	v_mov_b32_e32 v21, v80
	v_mov_b32_e32 v22, v80
	v_mov_b32_e32 v23, v80
	v_mov_b32_e32 v32, v80
	v_mov_b32_e32 v33, v80
	v_mov_b32_e32 v34, v80
	v_mov_b32_e32 v35, v80
	v_mov_b32_e32 v36, v80
	v_mov_b32_e32 v37, v80
	v_mov_b32_e32 v38, v80
	v_mov_b32_e32 v39, v80
	v_mov_b32_e32 v40, v80
	v_mov_b32_e32 v41, v80
	v_mov_b32_e32 v42, v80
	v_mov_b32_e32 v43, v80
	v_mov_b32_e32 v44, v80
	v_mov_b32_e32 v45, v80
	v_mov_b32_e32 v46, v80
	v_mov_b32_e32 v47, v80
	v_mov_b32_e32 v120, v80
	v_mov_b32_e32 v121, v80
	v_mov_b32_e32 v122, v80
	v_mov_b32_e32 v123, v80
	v_mov_b32_e32 v124, v80
	v_mov_b32_e32 v125, v80
	v_mov_b32_e32 v126, v80
	v_mov_b32_e32 v127, v80
	v_mov_b32_e32 v128, v80
	v_mov_b32_e32 v129, v80
	v_mov_b32_e32 v130, v80
	v_mov_b32_e32 v131, v80
	v_mov_b32_e32 v132, v80
	v_mov_b32_e32 v133, v80
	v_mov_b32_e32 v134, v80
	v_mov_b32_e32 v135, v80
	v_mov_b32_e32 v136, v80
	v_mov_b32_e32 v137, v80
	v_mov_b32_e32 v138, v80
	v_mov_b32_e32 v139, v80
	v_mov_b32_e32 v140, v80
	v_mov_b32_e32 v141, v80
	v_mov_b32_e32 v142, v80
	v_mov_b32_e32 v143, v80
	v_mov_b32_e32 v144, v80
	v_mov_b32_e32 v145, v80
	v_mov_b32_e32 v146, v80
	v_mov_b32_e32 v147, v80
	v_mov_b32_e32 v148, v80
	v_mov_b32_e32 v149, v80
	v_mov_b32_e32 v150, v80
	v_mov_b32_e32 v151, v80
	v_mov_b32_e32 v48, v80
	v_mov_b32_e32 v49, v80
	v_mov_b32_e32 v50, v80
	v_mov_b32_e32 v51, v80
	v_mov_b32_e32 v52, v80
	v_mov_b32_e32 v53, v80
	v_mov_b32_e32 v54, v80
	v_mov_b32_e32 v55, v80
	v_mov_b32_e32 v56, v80
	v_mov_b32_e32 v57, v80
	v_mov_b32_e32 v58, v80
	v_mov_b32_e32 v59, v80
	v_mov_b32_e32 v60, v80
	v_mov_b32_e32 v61, v80
	v_mov_b32_e32 v62, v80
	v_mov_b32_e32 v63, v80
	v_mov_b32_e32 v64, v80
	v_mov_b32_e32 v65, v80
	v_mov_b32_e32 v66, v80
	v_mov_b32_e32 v67, v80
	v_mov_b32_e32 v68, v80
	v_mov_b32_e32 v69, v80
	v_mov_b32_e32 v70, v80
	v_mov_b32_e32 v71, v80
	v_mov_b32_e32 v72, v80
	v_mov_b32_e32 v73, v80
	v_mov_b32_e32 v74, v80
	v_mov_b32_e32 v75, v80
	v_mov_b32_e32 v76, v80
	v_mov_b32_e32 v77, v80
	v_mov_b32_e32 v78, v80
	v_mov_b32_e32 v79, v80

.LBB0_255:
	s_cmp_eq_u32 s101, 2
	s_cbranch_scc1 .Lg1t_ret
	s_waitcnt vmcnt(0)
	s_waitcnt vmcnt(0) lgkmcnt(0)
	s_barrier
	s_mov_b64 s[0:1], exec
	v_readlane_b32 s4, v248, 18
	v_readlane_b32 s5, v248, 19
	s_and_b64 s[4:5], s[0:1], s[4:5]
	s_mov_b64 exec, s[4:5]
	s_cbranch_execz .LBB0_307
	v_readlane_b32 s4, v251, 2
	s_waitcnt vmcnt(0) expcnt(0) lgkmcnt(0)
	s_nop 0
	v_mov_b32_e32 v1, s4
	ds_read_b32 v3, v1
	v_readlane_b32 s4, v251, 3
	s_waitcnt lgkmcnt(0)
	v_cmp_ne_u32_e32 vcc, 0, v3
	v_mov_b32_e32 v1, s4
	ds_read_b32 v2, v1
	s_cbranch_vccnz .LBB0_271
	s_mov_b32 s10, 1
	s_branch .LBB0_259

.LBB0_651:
	s_sub_u32 s0, s72, 64
	s_cmp_lt_u32 s0, 128
	s_cbranch_scc0 .Lg1t_skip
	v_readlane_b32 s1, v248, 42
	v_readlane_b32 s2, v250, 7
	v_readlane_b32 s3, v250, 8
	v_readlane_b32 s4, v250, 9
	v_readlane_b32 s5, v250, 11
	v_readlane_b32 s6, v250, 12
	s_nop 3
	v_writelane_b32 v255, s1, 13
	v_writelane_b32 v255, s2, 14
	v_writelane_b32 v255, s3, 15
	v_writelane_b32 v255, s4, 16
	v_writelane_b32 v255, s5, 17
	v_writelane_b32 v255, s6, 18
	s_cmp_lt_u32 s0, 64
	s_cselect_b32 s1, 20, 17
	s_and_b32 s2, s0, 7
	s_lshl_b32 s2, s2, 3
	s_bfe_u32 s3, s0, 0x30003
	s_add_u32 s2, s2, s3
	s_lshl_b32 s3, s1, 19
	s_lshl_b32 s4, s2, 19
	s_mov_b32 s5, 0
	v_writelane_b32 v248, s1, 42
	v_writelane_b32 v250, s3, 7
	v_writelane_b32 v250, s5, 8
	v_writelane_b32 v250, s2, 9
	v_writelane_b32 v250, s4, 11
	v_writelane_b32 v250, s5, 12
	s_mov_b32 s74, 0x100000
	s_mov_b32 s101, 2
	v_readlane_b32 s4, v252, 7
	s_branch .LBB0_153
.Lg1t_ret:
	s_mov_b32 s101, 0
	v_readlane_b32 s1, v255, 13
	v_readlane_b32 s2, v255, 14
	v_readlane_b32 s3, v255, 15
	v_readlane_b32 s4, v255, 16
	v_readlane_b32 s5, v255, 17
	v_readlane_b32 s6, v255, 18
	s_nop 3
	v_writelane_b32 v248, s1, 42
	v_writelane_b32 v250, s2, 7
	v_writelane_b32 v250, s3, 8
	v_writelane_b32 v250, s4, 9
	v_writelane_b32 v250, s5, 11
	v_writelane_b32 v250, s6, 12
	v_readlane_b32 s74, v251, 34
	v_readlane_b32 s75, v251, 35
